# stack2 + code placement: the five GEMM K-loop back-edge targets aligned to 64 bytes
# baseline (speedup 1.0000x reference)
.LBB8_265:
	s_ashr_i32 s17, s16, 31
	s_lshl_b64 s[60:61], s[16:17], 21
	s_add_u32 s60, s54, s60
	s_addc_u32 s61, s55, s61
	s_and_b64 s[64:65], s[0:1], exec
	s_cselect_b32 s17, s61, s71
	s_cselect_b32 s85, s60, s70
	s_ashr_i32 s15, s14, 31
	s_lshl_b64 s[64:65], s[14:15], 21
	s_add_u32 s64, s4, s64
	s_addc_u32 s65, s5, s65
	s_and_b64 s[72:73], s[0:1], exec
	s_cselect_b32 s15, s65, s29
	s_cselect_b32 s86, s64, s28
	s_add_u32 s70, s70, 0x100080
	s_addc_u32 s71, s71, 0
	s_add_u32 s87, s28, 0x100
	v_mov_b32_e32 v0, 0
	s_addc_u32 s92, s29, 0
	s_mov_b32 s93, -2
	v_mov_b32_e32 v1, v0
	v_mov_b32_e32 v2, v0
	v_mov_b32_e32 v3, v0
	v_mov_b32_e32 v4, v0
	v_mov_b32_e32 v5, v0
	v_mov_b32_e32 v6, v0
	v_mov_b32_e32 v7, v0
	v_mov_b32_e32 v8, v0
	v_mov_b32_e32 v9, v0
	v_mov_b32_e32 v10, v0
	v_mov_b32_e32 v11, v0
	v_mov_b32_e32 v16, v0
	v_mov_b32_e32 v17, v0
	v_mov_b32_e32 v18, v0
	v_mov_b32_e32 v19, v0
	v_mov_b32_e32 v24, v0
	v_mov_b32_e32 v25, v0
	v_mov_b32_e32 v26, v0
	v_mov_b32_e32 v27, v0
	v_mov_b32_e32 v32, v0
	v_mov_b32_e32 v33, v0
	v_mov_b32_e32 v34, v0
	v_mov_b32_e32 v35, v0
	v_mov_b32_e32 v40, v0
	v_mov_b32_e32 v41, v0
	v_mov_b32_e32 v42, v0
	v_mov_b32_e32 v43, v0
	v_mov_b32_e32 v48, v0
	v_mov_b32_e32 v49, v0
	v_mov_b32_e32 v50, v0
	v_mov_b32_e32 v51, v0
	v_mov_b32_e32 v12, v0
	v_mov_b32_e32 v13, v0
	v_mov_b32_e32 v14, v0
	v_mov_b32_e32 v15, v0
	v_mov_b32_e32 v20, v0
	v_mov_b32_e32 v21, v0
	v_mov_b32_e32 v22, v0
	v_mov_b32_e32 v23, v0
	v_mov_b32_e32 v28, v0
	v_mov_b32_e32 v29, v0
	v_mov_b32_e32 v30, v0
	v_mov_b32_e32 v31, v0
	v_mov_b32_e32 v36, v0
	v_mov_b32_e32 v37, v0
	v_mov_b32_e32 v38, v0
	v_mov_b32_e32 v39, v0
	v_mov_b32_e32 v44, v0
	v_mov_b32_e32 v45, v0
	v_mov_b32_e32 v46, v0
	v_mov_b32_e32 v47, v0
	v_mov_b32_e32 v52, v0
	v_mov_b32_e32 v53, v0
	v_mov_b32_e32 v54, v0
	v_mov_b32_e32 v55, v0
	v_mov_b32_e32 v56, v0
	v_mov_b32_e32 v57, v0
	v_mov_b32_e32 v58, v0
	v_mov_b32_e32 v59, v0
	v_mov_b32_e32 v60, v0
	v_mov_b32_e32 v61, v0
	v_mov_b32_e32 v62, v0
	v_mov_b32_e32 v63, v0
	v_mov_b32_e32 v64, v0
	v_mov_b32_e32 v65, v0
	v_mov_b32_e32 v66, v0
	v_mov_b32_e32 v67, v0
	v_mov_b32_e32 v68, v0
	v_mov_b32_e32 v69, v0
	v_mov_b32_e32 v70, v0
	v_mov_b32_e32 v71, v0
	v_mov_b32_e32 v72, v0
	v_mov_b32_e32 v73, v0
	v_mov_b32_e32 v74, v0
	v_mov_b32_e32 v75, v0
	v_mov_b32_e32 v80, v0
	v_mov_b32_e32 v81, v0
	v_mov_b32_e32 v82, v0
	v_mov_b32_e32 v83, v0
	v_mov_b32_e32 v88, v0
	v_mov_b32_e32 v89, v0
	v_mov_b32_e32 v90, v0
	v_mov_b32_e32 v91, v0
	v_mov_b32_e32 v96, v0
	v_mov_b32_e32 v97, v0
	v_mov_b32_e32 v98, v0
	v_mov_b32_e32 v99, v0
	v_mov_b32_e32 v104, v0
	v_mov_b32_e32 v105, v0
	v_mov_b32_e32 v106, v0
	v_mov_b32_e32 v107, v0
	v_mov_b32_e32 v112, v0
	v_mov_b32_e32 v113, v0
	v_mov_b32_e32 v114, v0
	v_mov_b32_e32 v115, v0
	v_mov_b32_e32 v76, v0
	v_mov_b32_e32 v77, v0
	v_mov_b32_e32 v78, v0
	v_mov_b32_e32 v79, v0
	v_mov_b32_e32 v84, v0
	v_mov_b32_e32 v85, v0
	v_mov_b32_e32 v86, v0
	v_mov_b32_e32 v87, v0
	v_mov_b32_e32 v92, v0
	v_mov_b32_e32 v93, v0
	v_mov_b32_e32 v94, v0
	v_mov_b32_e32 v95, v0
	v_mov_b32_e32 v100, v0
	v_mov_b32_e32 v101, v0
	v_mov_b32_e32 v102, v0
	v_mov_b32_e32 v103, v0
	v_mov_b32_e32 v108, v0
	v_mov_b32_e32 v109, v0
	v_mov_b32_e32 v110, v0
	v_mov_b32_e32 v111, v0
	v_mov_b32_e32 v116, v0
	v_mov_b32_e32 v117, v0
	v_mov_b32_e32 v118, v0
	v_mov_b32_e32 v119, v0
	v_mov_b32_e32 v120, v0
	v_mov_b32_e32 v121, v0
	v_mov_b32_e32 v122, v0
	v_mov_b32_e32 v123, v0
	v_mov_b32_e32 v124, v0
	v_mov_b32_e32 v125, v0
	v_mov_b32_e32 v126, v0
	v_mov_b32_e32 v127, v0
	.p2align 6

.LBB8_843:
	s_ashr_i32 s17, s16, 31
	s_lshl_b64 s[18:19], s[16:17], 20
	s_add_u32 s18, s70, s18
	s_addc_u32 s19, s71, s19
	s_and_b64 s[20:21], s[0:1], exec
	s_cselect_b32 s5, s19, s25
	s_cselect_b32 s17, s18, s24
	s_ashr_i32 s15, s14, 31
	s_lshl_b64 s[20:21], s[14:15], 20
	s_add_u32 s20, s90, s20
	s_addc_u32 s21, s91, s21
	s_and_b64 s[34:35], s[0:1], exec
	s_cselect_b32 s15, s21, s29
	s_cselect_b32 s23, s20, s28
	s_add_u32 s24, s24, 0x80080
	s_addc_u32 s25, s25, 0
	s_add_u32 s56, s28, 0x100
	v_mov_b32_e32 v0, 0
	s_addc_u32 s57, s29, 0
	s_mov_b32 s58, -2
	v_mov_b32_e32 v1, v0
	v_mov_b32_e32 v2, v0
	v_mov_b32_e32 v3, v0
	v_mov_b32_e32 v4, v0
	v_mov_b32_e32 v5, v0
	v_mov_b32_e32 v6, v0
	v_mov_b32_e32 v7, v0
	v_mov_b32_e32 v16, v0
	v_mov_b32_e32 v17, v0
	v_mov_b32_e32 v18, v0
	v_mov_b32_e32 v19, v0
	v_mov_b32_e32 v20, v0
	v_mov_b32_e32 v21, v0
	v_mov_b32_e32 v22, v0
	v_mov_b32_e32 v23, v0
	v_mov_b32_e32 v32, v0
	v_mov_b32_e32 v33, v0
	v_mov_b32_e32 v34, v0
	v_mov_b32_e32 v35, v0
	v_mov_b32_e32 v36, v0
	v_mov_b32_e32 v37, v0
	v_mov_b32_e32 v38, v0
	v_mov_b32_e32 v39, v0
	v_mov_b32_e32 v52, v0
	v_mov_b32_e32 v53, v0
	v_mov_b32_e32 v54, v0
	v_mov_b32_e32 v55, v0
	v_mov_b32_e32 v56, v0
	v_mov_b32_e32 v57, v0
	v_mov_b32_e32 v58, v0
	v_mov_b32_e32 v59, v0
	v_mov_b32_e32 v8, v0
	v_mov_b32_e32 v9, v0
	v_mov_b32_e32 v10, v0
	v_mov_b32_e32 v11, v0
	v_mov_b32_e32 v12, v0
	v_mov_b32_e32 v13, v0
	v_mov_b32_e32 v14, v0
	v_mov_b32_e32 v15, v0
	v_mov_b32_e32 v24, v0
	v_mov_b32_e32 v25, v0
	v_mov_b32_e32 v26, v0
	v_mov_b32_e32 v27, v0
	v_mov_b32_e32 v28, v0
	v_mov_b32_e32 v29, v0
	v_mov_b32_e32 v30, v0
	v_mov_b32_e32 v31, v0
	v_mov_b32_e32 v40, v0
	v_mov_b32_e32 v41, v0
	v_mov_b32_e32 v42, v0
	v_mov_b32_e32 v43, v0
	v_mov_b32_e32 v44, v0
	v_mov_b32_e32 v45, v0
	v_mov_b32_e32 v46, v0
	v_mov_b32_e32 v47, v0
	v_mov_b32_e32 v64, v0
	v_mov_b32_e32 v65, v0
	v_mov_b32_e32 v66, v0
	v_mov_b32_e32 v67, v0
	v_mov_b32_e32 v68, v0
	v_mov_b32_e32 v69, v0
	v_mov_b32_e32 v70, v0
	v_mov_b32_e32 v71, v0
	v_mov_b32_e32 v76, v0
	v_mov_b32_e32 v77, v0
	v_mov_b32_e32 v78, v0
	v_mov_b32_e32 v79, v0
	v_mov_b32_e32 v84, v0
	v_mov_b32_e32 v85, v0
	v_mov_b32_e32 v86, v0
	v_mov_b32_e32 v87, v0
	v_mov_b32_e32 v104, v0
	v_mov_b32_e32 v105, v0
	v_mov_b32_e32 v106, v0
	v_mov_b32_e32 v107, v0
	v_mov_b32_e32 v108, v0
	v_mov_b32_e32 v109, v0
	v_mov_b32_e32 v110, v0
	v_mov_b32_e32 v111, v0
	v_mov_b32_e32 v128, v0
	v_mov_b32_e32 v129, v0
	v_mov_b32_e32 v130, v0
	v_mov_b32_e32 v131, v0
	v_mov_b32_e32 v132, v0
	v_mov_b32_e32 v133, v0
	v_mov_b32_e32 v134, v0
	v_mov_b32_e32 v135, v0
	v_mov_b32_e32 v148, v0
	v_mov_b32_e32 v149, v0
	v_mov_b32_e32 v150, v0
	v_mov_b32_e32 v151, v0
	v_mov_b32_e32 v152, v0
	v_mov_b32_e32 v153, v0
	v_mov_b32_e32 v154, v0
	v_mov_b32_e32 v155, v0
	v_mov_b32_e32 v92, v0
	v_mov_b32_e32 v93, v0
	v_mov_b32_e32 v94, v0
	v_mov_b32_e32 v95, v0
	v_mov_b32_e32 v96, v0
	v_mov_b32_e32 v97, v0
	v_mov_b32_e32 v98, v0
	v_mov_b32_e32 v99, v0
	v_mov_b32_e32 v116, v0
	v_mov_b32_e32 v117, v0
	v_mov_b32_e32 v118, v0
	v_mov_b32_e32 v119, v0
	v_mov_b32_e32 v120, v0
	v_mov_b32_e32 v121, v0
	v_mov_b32_e32 v122, v0
	v_mov_b32_e32 v123, v0
	v_mov_b32_e32 v136, v0
	v_mov_b32_e32 v137, v0
	v_mov_b32_e32 v138, v0
	v_mov_b32_e32 v139, v0
	v_mov_b32_e32 v140, v0
	v_mov_b32_e32 v141, v0
	v_mov_b32_e32 v142, v0
	v_mov_b32_e32 v143, v0
	v_mov_b32_e32 v160, v0
	v_mov_b32_e32 v161, v0
	v_mov_b32_e32 v162, v0
	v_mov_b32_e32 v163, v0
	v_mov_b32_e32 v164, v0
	v_mov_b32_e32 v165, v0
	v_mov_b32_e32 v166, v0
	v_mov_b32_e32 v167, v0
	.p2align 6

.LBB8_960:
	s_ashr_i32 s19, s18, 31
	s_lshl_b64 s[20:21], s[18:19], 21
	s_add_u32 s20, s64, s20
	s_addc_u32 s21, s65, s21
	s_and_b64 s[22:23], s[4:5], exec
	s_cselect_b32 s19, s21, s41
	s_cselect_b32 s25, s20, s40
	s_ashr_i32 s17, s16, 31
	s_lshl_b64 s[22:23], s[16:17], 21
	v_readlane_b32 s42, v254, 43
	v_readlane_b32 s43, v254, 44
	s_add_u32 s22, s42, s22
	s_addc_u32 s23, s43, s23
	s_and_b64 s[42:43], s[4:5], exec
	s_cselect_b32 s17, s23, s29
	s_cselect_b32 s66, s22, s28
	s_add_u32 s40, s40, 0x100080
	s_addc_u32 s41, s41, 0
	s_add_u32 s67, s28, 0x100
	v_mov_b32_e32 v0, 0
	s_addc_u32 s68, s29, 0
	s_mov_b32 s69, -2
	s_waitcnt lgkmcnt(0)
	v_mov_b32_e32 v1, v0
	v_mov_b32_e32 v2, v0
	v_mov_b32_e32 v3, v0
	v_mov_b32_e32 v4, v0
	v_mov_b32_e32 v5, v0
	v_mov_b32_e32 v6, v0
	v_mov_b32_e32 v7, v0
	v_mov_b32_e32 v16, v0
	v_mov_b32_e32 v17, v0
	v_mov_b32_e32 v18, v0
	v_mov_b32_e32 v19, v0
	v_mov_b32_e32 v20, v0
	v_mov_b32_e32 v21, v0
	v_mov_b32_e32 v22, v0
	v_mov_b32_e32 v23, v0
	v_mov_b32_e32 v32, v0
	v_mov_b32_e32 v33, v0
	v_mov_b32_e32 v34, v0
	v_mov_b32_e32 v35, v0
	v_mov_b32_e32 v36, v0
	v_mov_b32_e32 v37, v0
	v_mov_b32_e32 v38, v0
	v_mov_b32_e32 v39, v0
	v_mov_b32_e32 v48, v0
	v_mov_b32_e32 v49, v0
	v_mov_b32_e32 v50, v0
	v_mov_b32_e32 v51, v0
	v_mov_b32_e32 v52, v0
	v_mov_b32_e32 v53, v0
	v_mov_b32_e32 v54, v0
	v_mov_b32_e32 v55, v0
	v_mov_b32_e32 v8, v0
	v_mov_b32_e32 v9, v0
	v_mov_b32_e32 v10, v0
	v_mov_b32_e32 v11, v0
	v_mov_b32_e32 v12, v0
	v_mov_b32_e32 v13, v0
	v_mov_b32_e32 v14, v0
	v_mov_b32_e32 v15, v0
	v_mov_b32_e32 v24, v0
	v_mov_b32_e32 v25, v0
	v_mov_b32_e32 v26, v0
	v_mov_b32_e32 v27, v0
	v_mov_b32_e32 v28, v0
	v_mov_b32_e32 v29, v0
	v_mov_b32_e32 v30, v0
	v_mov_b32_e32 v31, v0
	v_mov_b32_e32 v40, v0
	v_mov_b32_e32 v41, v0
	v_mov_b32_e32 v42, v0
	v_mov_b32_e32 v43, v0
	v_mov_b32_e32 v44, v0
	v_mov_b32_e32 v45, v0
	v_mov_b32_e32 v46, v0
	v_mov_b32_e32 v47, v0
	v_mov_b32_e32 v56, v0
	v_mov_b32_e32 v57, v0
	v_mov_b32_e32 v58, v0
	v_mov_b32_e32 v59, v0
	v_mov_b32_e32 v60, v0
	v_mov_b32_e32 v61, v0
	v_mov_b32_e32 v62, v0
	v_mov_b32_e32 v63, v0
	v_mov_b32_e32 v64, v0
	v_mov_b32_e32 v65, v0
	v_mov_b32_e32 v66, v0
	v_mov_b32_e32 v67, v0
	v_mov_b32_e32 v68, v0
	v_mov_b32_e32 v69, v0
	v_mov_b32_e32 v70, v0
	v_mov_b32_e32 v71, v0
	v_mov_b32_e32 v92, v0
	v_mov_b32_e32 v93, v0
	v_mov_b32_e32 v94, v0
	v_mov_b32_e32 v95, v0
	v_mov_b32_e32 v100, v0
	v_mov_b32_e32 v101, v0
	v_mov_b32_e32 v102, v0
	v_mov_b32_e32 v103, v0
	v_mov_b32_e32 v112, v0
	v_mov_b32_e32 v113, v0
	v_mov_b32_e32 v114, v0
	v_mov_b32_e32 v115, v0
	v_mov_b32_e32 v116, v0
	v_mov_b32_e32 v117, v0
	v_mov_b32_e32 v118, v0
	v_mov_b32_e32 v119, v0
	v_mov_b32_e32 v128, v0
	v_mov_b32_e32 v129, v0
	v_mov_b32_e32 v130, v0
	v_mov_b32_e32 v131, v0
	v_mov_b32_e32 v132, v0
	v_mov_b32_e32 v133, v0
	v_mov_b32_e32 v134, v0
	v_mov_b32_e32 v135, v0
	v_mov_b32_e32 v72, v0
	v_mov_b32_e32 v73, v0
	v_mov_b32_e32 v74, v0
	v_mov_b32_e32 v75, v0
	v_mov_b32_e32 v80, v0
	v_mov_b32_e32 v81, v0
	v_mov_b32_e32 v82, v0
	v_mov_b32_e32 v83, v0
	v_mov_b32_e32 v104, v0
	v_mov_b32_e32 v105, v0
	v_mov_b32_e32 v106, v0
	v_mov_b32_e32 v107, v0
	v_mov_b32_e32 v108, v0
	v_mov_b32_e32 v109, v0
	v_mov_b32_e32 v110, v0
	v_mov_b32_e32 v111, v0
	v_mov_b32_e32 v120, v0
	v_mov_b32_e32 v121, v0
	v_mov_b32_e32 v122, v0
	v_mov_b32_e32 v123, v0
	v_mov_b32_e32 v124, v0
	v_mov_b32_e32 v125, v0
	v_mov_b32_e32 v126, v0
	v_mov_b32_e32 v127, v0
	v_mov_b32_e32 v136, v0
	v_mov_b32_e32 v137, v0
	v_mov_b32_e32 v138, v0
	v_mov_b32_e32 v139, v0
	v_mov_b32_e32 v140, v0
	v_mov_b32_e32 v141, v0
	v_mov_b32_e32 v142, v0
	v_mov_b32_e32 v143, v0
	.p2align 6

.LBB8_1051:
	s_ashr_i32 s25, s24, 31
	s_lshl_b64 s[34:35], s[24:25], 21
	s_add_u32 s34, s54, s34
	s_addc_u32 s35, s55, s35
	s_and_b64 s[40:41], s[0:1], exec
	s_cselect_b32 s25, s35, s45
	s_cselect_b32 s63, s34, s44
	s_ashr_i32 s23, s22, 31
	s_lshl_b64 s[40:41], s[22:23], 21
	s_add_u32 s40, s92, s40
	s_addc_u32 s41, s93, s41
	s_and_b64 s[64:65], s[0:1], exec
	s_cselect_b32 s23, s41, s29
	s_cselect_b32 s64, s40, s28
	v_lshl_or_b32 v160, s43, 8, v168
	s_ashr_i32 s43, s42, 31
	s_lshr_b32 s43, s43, 29
	v_lshl_add_u32 v158, s42, 8, v166
	s_add_i32 s42, s42, s43
	s_ashr_i32 s42, s42, 3
	s_ashr_i32 s43, s42, 31
	s_lshl_b64 s[42:43], s[42:43], 16
	s_add_u32 s42, s26, s42
	v_ashrrev_i32_e32 v161, 31, v160
	s_addc_u32 s43, s27, s43
	v_lshl_add_u64 v[162:163], v[160:161], 2, s[42:43]
	s_add_u32 s42, s44, 0x100080
	s_addc_u32 s43, s45, 0
	v_ashrrev_i32_e32 v159, 31, v158
	s_add_u32 s65, s28, 0x100
	v_mov_b32_e32 v16, 0
	v_lshl_add_u64 v[164:165], v[158:159], 2, s[6:7]
	s_addc_u32 s66, s29, 0
	s_mov_b32 s67, -2
	v_mov_b32_e32 v17, v16
	v_mov_b32_e32 v18, v16
	v_mov_b32_e32 v19, v16
	v_mov_b32_e32 v20, v16
	v_mov_b32_e32 v21, v16
	v_mov_b32_e32 v22, v16
	v_mov_b32_e32 v23, v16
	v_mov_b32_e32 v32, v16
	v_mov_b32_e32 v33, v16
	v_mov_b32_e32 v34, v16
	v_mov_b32_e32 v35, v16
	v_mov_b32_e32 v36, v16
	v_mov_b32_e32 v37, v16
	v_mov_b32_e32 v38, v16
	v_mov_b32_e32 v39, v16
	v_mov_b32_e32 v48, v16
	v_mov_b32_e32 v49, v16
	v_mov_b32_e32 v50, v16
	v_mov_b32_e32 v51, v16
	v_mov_b32_e32 v52, v16
	v_mov_b32_e32 v53, v16
	v_mov_b32_e32 v54, v16
	v_mov_b32_e32 v55, v16
	v_mov_b32_e32 v64, v16
	v_mov_b32_e32 v65, v16
	v_mov_b32_e32 v66, v16
	v_mov_b32_e32 v67, v16
	v_mov_b32_e32 v68, v16
	v_mov_b32_e32 v69, v16
	v_mov_b32_e32 v70, v16
	v_mov_b32_e32 v71, v16
	v_mov_b32_e32 v24, v16
	v_mov_b32_e32 v25, v16
	v_mov_b32_e32 v26, v16
	v_mov_b32_e32 v27, v16
	v_mov_b32_e32 v28, v16
	v_mov_b32_e32 v29, v16
	v_mov_b32_e32 v30, v16
	v_mov_b32_e32 v31, v16
	v_mov_b32_e32 v40, v16
	v_mov_b32_e32 v41, v16
	v_mov_b32_e32 v42, v16
	v_mov_b32_e32 v43, v16
	v_mov_b32_e32 v44, v16
	v_mov_b32_e32 v45, v16
	v_mov_b32_e32 v46, v16
	v_mov_b32_e32 v47, v16
	v_mov_b32_e32 v56, v16
	v_mov_b32_e32 v57, v16
	v_mov_b32_e32 v58, v16
	v_mov_b32_e32 v59, v16
	v_mov_b32_e32 v60, v16
	v_mov_b32_e32 v61, v16
	v_mov_b32_e32 v62, v16
	v_mov_b32_e32 v63, v16
	v_mov_b32_e32 v72, v16
	v_mov_b32_e32 v73, v16
	v_mov_b32_e32 v74, v16
	v_mov_b32_e32 v75, v16
	v_mov_b32_e32 v76, v16
	v_mov_b32_e32 v77, v16
	v_mov_b32_e32 v78, v16
	v_mov_b32_e32 v79, v16
	v_mov_b32_e32 v80, v16
	v_mov_b32_e32 v81, v16
	v_mov_b32_e32 v82, v16
	v_mov_b32_e32 v83, v16
	v_mov_b32_e32 v84, v16
	v_mov_b32_e32 v85, v16
	v_mov_b32_e32 v86, v16
	v_mov_b32_e32 v87, v16
	v_mov_b32_e32 v96, v16
	v_mov_b32_e32 v97, v16
	v_mov_b32_e32 v98, v16
	v_mov_b32_e32 v99, v16
	v_mov_b32_e32 v100, v16
	v_mov_b32_e32 v101, v16
	v_mov_b32_e32 v102, v16
	v_mov_b32_e32 v103, v16
	v_mov_b32_e32 v112, v16
	v_mov_b32_e32 v113, v16
	v_mov_b32_e32 v114, v16
	v_mov_b32_e32 v115, v16
	v_mov_b32_e32 v116, v16
	v_mov_b32_e32 v117, v16
	v_mov_b32_e32 v118, v16
	v_mov_b32_e32 v119, v16
	v_mov_b32_e32 v128, v16
	v_mov_b32_e32 v129, v16
	v_mov_b32_e32 v130, v16
	v_mov_b32_e32 v131, v16
	v_mov_b32_e32 v132, v16
	v_mov_b32_e32 v133, v16
	v_mov_b32_e32 v134, v16
	v_mov_b32_e32 v135, v16
	v_mov_b32_e32 v88, v16
	v_mov_b32_e32 v89, v16
	v_mov_b32_e32 v90, v16
	v_mov_b32_e32 v91, v16
	v_mov_b32_e32 v92, v16
	v_mov_b32_e32 v93, v16
	v_mov_b32_e32 v94, v16
	v_mov_b32_e32 v95, v16
	v_mov_b32_e32 v104, v16
	v_mov_b32_e32 v105, v16
	v_mov_b32_e32 v106, v16
	v_mov_b32_e32 v107, v16
	v_mov_b32_e32 v108, v16
	v_mov_b32_e32 v109, v16
	v_mov_b32_e32 v110, v16
	v_mov_b32_e32 v111, v16
	v_mov_b32_e32 v120, v16
	v_mov_b32_e32 v121, v16
	v_mov_b32_e32 v122, v16
	v_mov_b32_e32 v123, v16
	v_mov_b32_e32 v124, v16
	v_mov_b32_e32 v125, v16
	v_mov_b32_e32 v126, v16
	v_mov_b32_e32 v127, v16
	v_mov_b32_e32 v136, v16
	v_mov_b32_e32 v137, v16
	v_mov_b32_e32 v138, v16
	v_mov_b32_e32 v139, v16
	v_mov_b32_e32 v140, v16
	v_mov_b32_e32 v141, v16
	v_mov_b32_e32 v142, v16
	v_mov_b32_e32 v143, v16
	s_branch .LBB8_1053
	.p2align 6

.LBB8_1132:
	s_ashr_i32 s21, s20, 31
	s_lshl_b64 s[22:23], s[20:21], 23
	s_add_u32 s22, s36, s22
	s_addc_u32 s23, s37, s23
	s_and_b64 s[24:25], s[0:1], exec
	s_cselect_b32 s21, s23, s35
	s_cselect_b32 s53, s22, s34
	s_ashr_i32 s19, s18, 31
	s_lshl_b64 s[24:25], s[18:19], 23
	s_add_u32 s24, s88, s24
	s_addc_u32 s25, s89, s25
	s_and_b64 s[26:27], s[0:1], exec
	s_cselect_b32 s19, s25, s31
	s_cselect_b32 s54, s24, s30
	s_add_u32 s26, s34, 0x400080
	s_addc_u32 s27, s35, 0
	s_add_u32 s55, s30, 0x100
	v_mov_b32_e32 v0, 0
	s_addc_u32 s56, s31, 0
	s_mov_b32 s57, -2
	v_mov_b32_e32 v1, v0
	v_mov_b32_e32 v2, v0
	v_mov_b32_e32 v3, v0
	v_mov_b32_e32 v4, v0
	v_mov_b32_e32 v5, v0
	v_mov_b32_e32 v6, v0
	v_mov_b32_e32 v7, v0
	v_mov_b32_e32 v8, v0
	v_mov_b32_e32 v9, v0
	v_mov_b32_e32 v10, v0
	v_mov_b32_e32 v11, v0
	v_mov_b32_e32 v16, v0
	v_mov_b32_e32 v17, v0
	v_mov_b32_e32 v18, v0
	v_mov_b32_e32 v19, v0
	v_mov_b32_e32 v24, v0
	v_mov_b32_e32 v25, v0
	v_mov_b32_e32 v26, v0
	v_mov_b32_e32 v27, v0
	v_mov_b32_e32 v32, v0
	v_mov_b32_e32 v33, v0
	v_mov_b32_e32 v34, v0
	v_mov_b32_e32 v35, v0
	v_mov_b32_e32 v40, v0
	v_mov_b32_e32 v41, v0
	v_mov_b32_e32 v42, v0
	v_mov_b32_e32 v43, v0
	v_mov_b32_e32 v48, v0
	v_mov_b32_e32 v49, v0
	v_mov_b32_e32 v50, v0
	v_mov_b32_e32 v51, v0
	v_mov_b32_e32 v12, v0
	v_mov_b32_e32 v13, v0
	v_mov_b32_e32 v14, v0
	v_mov_b32_e32 v15, v0
	v_mov_b32_e32 v20, v0
	v_mov_b32_e32 v21, v0
	v_mov_b32_e32 v22, v0
	v_mov_b32_e32 v23, v0
	v_mov_b32_e32 v28, v0
	v_mov_b32_e32 v29, v0
	v_mov_b32_e32 v30, v0
	v_mov_b32_e32 v31, v0
	v_mov_b32_e32 v36, v0
	v_mov_b32_e32 v37, v0
	v_mov_b32_e32 v38, v0
	v_mov_b32_e32 v39, v0
	v_mov_b32_e32 v44, v0
	v_mov_b32_e32 v45, v0
	v_mov_b32_e32 v46, v0
	v_mov_b32_e32 v47, v0
	v_mov_b32_e32 v52, v0
	v_mov_b32_e32 v53, v0
	v_mov_b32_e32 v54, v0
	v_mov_b32_e32 v55, v0
	v_mov_b32_e32 v56, v0
	v_mov_b32_e32 v57, v0
	v_mov_b32_e32 v58, v0
	v_mov_b32_e32 v59, v0
	v_mov_b32_e32 v60, v0
	v_mov_b32_e32 v61, v0
	v_mov_b32_e32 v62, v0
	v_mov_b32_e32 v63, v0
	v_mov_b32_e32 v64, v0
	v_mov_b32_e32 v65, v0
	v_mov_b32_e32 v66, v0
	v_mov_b32_e32 v67, v0
	v_mov_b32_e32 v68, v0
	v_mov_b32_e32 v69, v0
	v_mov_b32_e32 v70, v0
	v_mov_b32_e32 v71, v0
	v_mov_b32_e32 v72, v0
	v_mov_b32_e32 v73, v0
	v_mov_b32_e32 v74, v0
	v_mov_b32_e32 v75, v0
	v_mov_b32_e32 v80, v0
	v_mov_b32_e32 v81, v0
	v_mov_b32_e32 v82, v0
	v_mov_b32_e32 v83, v0
	v_mov_b32_e32 v92, v0
	v_mov_b32_e32 v93, v0
	v_mov_b32_e32 v94, v0
	v_mov_b32_e32 v95, v0
	v_mov_b32_e32 v104, v0
	v_mov_b32_e32 v105, v0
	v_mov_b32_e32 v106, v0
	v_mov_b32_e32 v107, v0
	v_mov_b32_e32 v116, v0
	v_mov_b32_e32 v117, v0
	v_mov_b32_e32 v118, v0
	v_mov_b32_e32 v119, v0
	v_mov_b32_e32 v124, v0
	v_mov_b32_e32 v125, v0
	v_mov_b32_e32 v126, v0
	v_mov_b32_e32 v127, v0
	v_mov_b32_e32 v88, v0
	v_mov_b32_e32 v89, v0
	v_mov_b32_e32 v90, v0
	v_mov_b32_e32 v91, v0
	v_mov_b32_e32 v100, v0
	v_mov_b32_e32 v101, v0
	v_mov_b32_e32 v102, v0
	v_mov_b32_e32 v103, v0
	v_mov_b32_e32 v112, v0
	v_mov_b32_e32 v113, v0
	v_mov_b32_e32 v114, v0
	v_mov_b32_e32 v115, v0
	v_mov_b32_e32 v120, v0
	v_mov_b32_e32 v121, v0
	v_mov_b32_e32 v122, v0
	v_mov_b32_e32 v123, v0
	v_mov_b32_e32 v128, v0
	v_mov_b32_e32 v129, v0
	v_mov_b32_e32 v130, v0
	v_mov_b32_e32 v131, v0
	v_mov_b32_e32 v132, v0
	v_mov_b32_e32 v133, v0
	v_mov_b32_e32 v134, v0
	v_mov_b32_e32 v135, v0
	v_mov_b32_e32 v136, v0
	v_mov_b32_e32 v137, v0
	v_mov_b32_e32 v138, v0
	v_mov_b32_e32 v139, v0
	v_mov_b32_e32 v140, v0
	v_mov_b32_e32 v141, v0
	v_mov_b32_e32 v142, v0
	v_mov_b32_e32 v143, v0
	.p2align 6
